# final candidate: same as v40 with V-store/exp register distance restored at the B->A seam
# speedup vs baseline: 1.0038x; 1.0038x over previous
; #define SBAR() __builtin_amdgcn_sched_barrier(0)
; #define KWRITE(b, src0, src1) do { if constexpr (ND0 == 4) { *(bf16x8*)(K_lds + (b) * SHM_K + KSWZ(kr, kcb)) = src0; } \
;     else { int kc = sc * 2; *(bf16x8*)(K_lds + (b) * SHM_K + KSWZ(sr, kc)) = src0; *(bf16x8*)(K_lds + (b) * SHM_K + KSWZ(32 + sr, kc)) = src1; } } while (0)
; #define SLOAD_A(k0) do { vs0a = *reinterpret_cast<const bf16x8*>(&Vh[(long)((k0) + sr) * LDK + sc]); vs1a = *reinterpret_cast<const bf16x8*>(&Vh[(long)((k0) + 32 + sr) * LDK + sc]); KLOAD(ks0a, ks1a, k0); } while (0)
; #define SLOAD_B(k0) do { vs0b = *reinterpret_cast<const bf16x8*>(&Vh[(long)((k0) + sr) * LDK + sc]); vs1b = *reinterpret_cast<const bf16x8*>(&Vh[(long)((k0) + 32 + sr) * LDK + sc]); KLOAD(ks0b, ks1b, k0); } while (0)
; #define VWRITE_A(b) do { *(bf16x8*)(V_lds + (b) * SHM_V + vst0) = vs0a; *(bf16x8*)(V_lds + (b) * SHM_V + vst1) = vs1a; } while (0)
; #define VWRITE_B(b) do { *(bf16x8*)(V_lds + (b) * SHM_V + vst0) = vs0b; *(bf16x8*)(V_lds + (b) * SHM_V + vst1) = vs1b; } while (0)
; #define SWAIT() do { if constexpr (ND0 == 4) asm volatile("s_waitcnt vmcnt(3)" ::: "memory"); else asm volatile("s_waitcnt vmcnt(4)" ::: "memory"); } while (0)
; #define PSM(P0, P1, MN, AL) do { if constexpr (PRE) partialSM_pre(P0, P1, m_reg, AL, 11.541560327111707f); else partialSM(P0, P1, m_reg, MN, AL, C, thr_raw); } while (0)
; __device__ __forceinline__ void partialSM_pre(f32x16& p0, f32x16& p1, float& m_ref, float& alpha, const float thr2) {
;     ...
; #pragma unroll
;   for (int r = 0; r < 16; ++r) p0[r] = __builtin_amdgcn_exp2f(p0[r]);
; template <int ND0, int LDQ, int LDK, int LDO> ...
;     ...
;   for (int j = 1; j + 1 < NT; j += 2) {
;     SBAR(); qkt<ND0>(pB0, pB1, Kq1, qr, r32, hi);
;     finishSM(pA0, pA1, alA, l_reg, pa0, pa1, pa2, pa3); SBAR();
;     SLOAD_B((j + 2) * KVBLK); SBAR();
;     pv_d0(o, vb0, pa0, pa1, pa2, pa3); KWRITE(0, ks0a, ks1a); PSM(pB0, pB1, mnB, alB);
;     __syncthreads(); SWAIT(); VWRITE_A(0);
;     RESC(alB); __syncthreads();
;     SBAR(); qkt<ND0>(pA0, pA1, Kq0, qr, r32, hi);
;     finishSM(pB0, pB1, alB, l_reg, pa0, pa1, pa2, pa3); SBAR();
;     if (j + 3 < NT) SLOAD_A((j + 3) * KVBLK); SBAR();
;     pv_d0(o, vb0 + (int)SHM_V, pa0, pa1, pa2, pa3); KWRITE(1, ks0b, ks1b); PSM(pA0, pA1, mnA, alA);
;     __syncthreads(); SWAIT(); VWRITE_B(1);
;     RESC(alA); __syncthreads();
;   }
.LBB0_161:
	v_lshl_add_u64 v[188:189], v[188:189], 0, s[42:43]
	s_and_b64 vcc, exec, s[4:5]
	v_exp_f32_e32 v163, v108
	v_exp_f32_e32 v165, v109
	v_exp_f32_e32 v162, v110
	v_exp_f32_e32 v164, v111
	v_exp_f32_e32 v167, v104
	v_exp_f32_e32 v169, v105
	v_exp_f32_e32 v166, v106
	v_exp_f32_e32 v168, v107
	s_cbranch_vccnz .LBB0_167
	v_mov_b32_e32 v207, v170
	s_branch .LBB0_146

; #define SBAR() __builtin_amdgcn_sched_barrier(0)
; #define KWRITE(b, src0, src1) do { if constexpr (ND0 == 4) { *(bf16x8*)(K_lds + (b) * SHM_K + KSWZ(kr, kcb)) = src0; } \
;     else { int kc = sc * 2; *(bf16x8*)(K_lds + (b) * SHM_K + KSWZ(sr, kc)) = src0; *(bf16x8*)(K_lds + (b) * SHM_K + KSWZ(32 + sr, kc)) = src1; } } while (0)
; #define SLOAD_A(k0) do { vs0a = *reinterpret_cast<const bf16x8*>(&Vh[(long)((k0) + sr) * LDK + sc]); vs1a = *reinterpret_cast<const bf16x8*>(&Vh[(long)((k0) + 32 + sr) * LDK + sc]); KLOAD(ks0a, ks1a, k0); } while (0)
; #define SLOAD_B(k0) do { vs0b = *reinterpret_cast<const bf16x8*>(&Vh[(long)((k0) + sr) * LDK + sc]); vs1b = *reinterpret_cast<const bf16x8*>(&Vh[(long)((k0) + 32 + sr) * LDK + sc]); KLOAD(ks0b, ks1b, k0); } while (0)
; #define VWRITE_A(b) do { *(bf16x8*)(V_lds + (b) * SHM_V + vst0) = vs0a; *(bf16x8*)(V_lds + (b) * SHM_V + vst1) = vs1a; } while (0)
; #define VWRITE_B(b) do { *(bf16x8*)(V_lds + (b) * SHM_V + vst0) = vs0b; *(bf16x8*)(V_lds + (b) * SHM_V + vst1) = vs1b; } while (0)
; #define SWAIT() do { if constexpr (ND0 == 4) asm volatile("s_waitcnt vmcnt(3)" ::: "memory"); else asm volatile("s_waitcnt vmcnt(4)" ::: "memory"); } while (0)
; #define PSM(P0, P1, MN, AL) do { if constexpr (PRE) partialSM_pre(P0, P1, m_reg, AL, 11.541560327111707f); else partialSM(P0, P1, m_reg, MN, AL, C, thr_raw); } while (0)
; __device__ __forceinline__ void partialSM_pre(f32x16& p0, f32x16& p1, float& m_ref, float& alpha, const float thr2) {
;     ...
; #pragma unroll
;   for (int r = 0; r < 16; ++r) p0[r] = __builtin_amdgcn_exp2f(p0[r]);
; template <int ND0, int LDQ, int LDK, int LDO> ...
;     ...
;   for (int j = 1; j + 1 < NT; j += 2) {
;     SBAR(); qkt<ND0>(pB0, pB1, Kq1, qr, r32, hi);
;     finishSM(pA0, pA1, alA, l_reg, pa0, pa1, pa2, pa3); SBAR();
;     SLOAD_B((j + 2) * KVBLK); SBAR();
;     pv_d0(o, vb0, pa0, pa1, pa2, pa3); KWRITE(0, ks0a, ks1a); PSM(pB0, pB1, mnB, alB);
;     __syncthreads(); SWAIT(); VWRITE_A(0);
;     RESC(alB); __syncthreads();
;     SBAR(); qkt<ND0>(pA0, pA1, Kq0, qr, r32, hi);
;     finishSM(pB0, pB1, alB, l_reg, pa0, pa1, pa2, pa3); SBAR();
;     if (j + 3 < NT) SLOAD_A((j + 3) * KVBLK); SBAR();
;     pv_d0(o, vb0 + (int)SHM_V, pa0, pa1, pa2, pa3); KWRITE(1, ks0b, ks1b); PSM(pA0, pA1, mnA, alA);
;     __syncthreads(); SWAIT(); VWRITE_B(1);
;     RESC(alA); __syncthreads();
;   }
.LBB0_228:
	s_add_i32 s40, s40, 2
	s_and_b64 vcc, exec, s[18:19]
	v_exp_f32_e32 v143, v108
	v_exp_f32_e32 v142, v110
	v_exp_f32_e32 v144, v111
	v_exp_f32_e32 v145, v106
	v_exp_f32_e32 v147, v104
	v_exp_f32_e32 v149, v105
	v_exp_f32_e32 v148, v107
	v_exp_f32_e32 v146, v109
	s_cbranch_vccnz .LBB0_234
	v_mov_b32_e32 v200, v150
	s_branch .LBB0_214
